# adds P5 down epilogue: y f32 stores transposed through the LDS scratch (whole 128-B row segments per store), stores software-pipelined one step behind the LDS ops
# speedup vs baseline: 1.0288x; 1.0142x over previous
; __host__ __device__ __forceinline__ size_t img_off(int row, int col, int nkt) { return ((size_t)((row >> 7) * nkt + (col >> 6)) << 14) + (size_t)lds_byte(row & 127, col & 63); }
;     __device__ __forceinline__ void operator()(const f32x4 (&acc)[2][2][4][2], const Unit& u, int wr, int wc, int fr, int fq) const {
;         const int row0 = u.pm * BM + wr * 64 + fr; const int col0 = u.pn * BM + wc * 32 + 8 * fq; const char* x1b = (const char*)(ws + EW_X1B);
; #pragma unroll
;         for (int ai = 0; ai < 2; ++ai)
; #pragma unroll
;             for (int m = 0; m < 4; ++m) { const int row = row0 + ai * HALF + m * 16; const size_t off = (size_t)row * 1024 + col0;
; #pragma unroll
;                 for (int bj = 0; bj < 2; ++bj) { const u32x4 xb = __builtin_nontemporal_load((const u32x4*)(x1b + img_off(row, col0 + bj * HALF, 16))); float* p = y + off + bj * HALF;
;                     const f32x4 x0 = (f32x4){__builtin_bit_cast(float, xb.x << 16), __builtin_bit_cast(float, xb.x & 0xffff0000u), __builtin_bit_cast(float, xb.y << 16), __builtin_bit_cast(float, xb.y & 0xffff0000u)};
;                     const f32x4 x1 = (f32x4){__builtin_bit_cast(float, xb.z << 16), __builtin_bit_cast(float, xb.z & 0xffff0000u), __builtin_bit_cast(float, xb.w << 16), __builtin_bit_cast(float, xb.w & 0xffff0000u)};
;                     __builtin_nontemporal_store(acc[ai][bj][m][0] + x0, (f32x4*)p); __builtin_nontemporal_store(acc[ai][bj][m][1] + x1, (f32x4*)(p + 4)); } }
.LBB0_1427:
	s_lshl_b32 s13, s56, 8
	s_lshl_b32 s12, s55, 8
	s_or_b32 s13, s13, s45
	s_add_i32 s12, s12, s44
	v_or_b32_e32 v138, s13, v141
	v_or_b32_e32 v136, s12, v140
	v_lshlrev_b32_e32 v130, 1, v138
	s_bfe_u32 s55, s45, 0x10005
	v_and_b32_e32 v146, 48, v130
	s_ashr_i32 s12, s12, 3
	v_lshlrev_b32_e32 v130, 6, v136
	s_and_b32 s36, s12, -16
	s_ashr_i32 s57, s13, 6
	s_or_b32 s37, s55, s49
	v_and_or_b32 v147, v130, s48, v146
	v_lshlrev_b32_e32 v130, 2, v136
	s_add_i32 s12, s36, s57
	s_lshl_b32 s58, s37, 10
	v_and_b32_e32 v160, 32, v130
	s_ashr_i32 s13, s12, 31
	v_bitop3_b32 v130, v147, s58, v160 bitop3:0xde
	s_lshl_b64 s[12:13], s[12:13], 14
	v_lshl_add_u64 v[152:153], s[30:31], 0, v[130:131]
	v_lshl_add_u64 v[148:149], v[152:153], 0, s[12:13]
	s_mov_b64 s[98:99], 0x1000
	s_mov_b64 s[100:101], 0x8000
	v_lshl_add_u64 v[230:231], v[148:149], 0, s[98:99]
	v_lshl_add_u64 v[232:233], v[148:149], 0, s[100:101]
	v_lshl_add_u64 v[234:235], v[230:231], 0, s[100:101]
	s_mov_b64 s[100:101], 0x40000
	v_lshl_add_u64 v[236:237], v[148:149], 0, s[100:101]
	v_lshl_add_u64 v[238:239], v[230:231], 0, s[100:101]
	v_lshl_add_u64 v[240:241], v[232:233], 0, s[100:101]
	v_lshl_add_u64 v[242:243], v[234:235], 0, s[100:101]
	global_load_dwordx4 v[162:165], v[148:149], off nt
	global_load_dwordx4 v[166:169], v[232:233], off nt
	global_load_dwordx4 v[170:173], v[148:149], off offset:2048 nt
	global_load_dwordx4 v[174:177], v[232:233], off offset:2048 nt
	global_load_dwordx4 v[178:181], v[230:231], off nt
	global_load_dwordx4 v[182:185], v[234:235], off nt
	global_load_dwordx4 v[186:189], v[230:231], off offset:2048 nt
	global_load_dwordx4 v[190:193], v[234:235], off offset:2048 nt
	global_load_dwordx4 v[194:197], v[236:237], off nt
	global_load_dwordx4 v[202:205], v[240:241], off nt
	global_load_dwordx4 v[206:209], v[236:237], off offset:2048 nt
	global_load_dwordx4 v[210:213], v[240:241], off offset:2048 nt
	global_load_dwordx4 v[214:217], v[238:239], off nt
	global_load_dwordx4 v[218:221], v[242:243], off nt
	global_load_dwordx4 v[222:225], v[238:239], off offset:2048 nt
	global_load_dwordx4 v[226:229], v[242:243], off offset:2048 nt
	s_lshl_b32 s98, s44, 7
	s_lshl_b32 s99, s45, 6
	s_add_i32 s98, s98, s99
	s_add_i32 s98, s98, 0x24000
	v_and_b32_e32 v244, 15, v200
	v_lshrrev_b32_e32 v245, 4, v200
	v_and_b32_e32 v246, 3, v244
	v_xor_b32_e32 v246, v245, v246
	v_lshlrev_b32_e32 v246, 5, v246
	v_lshl_add_u32 v246, v244, 7, v246
	v_add_u32_e32 v248, s98, v246
	v_lshrrev_b32_e32 v244, 3, v200
	v_and_b32_e32 v245, 7, v200
	v_lshlrev_b32_e32 v161, 4, v245
	v_lshl_add_u32 v161, v244, 12, v161
	v_add_u32_e32 v201, 0x8000, v161
	v_lshrrev_b32_e32 v246, 1, v245
	v_and_b32_e32 v245, 1, v245
	v_and_b32_e32 v247, 3, v244
	v_xor_b32_e32 v246, v246, v247
	v_lshl_or_b32 v246, v246, 1, v245
	v_lshlrev_b32_e32 v246, 4, v246
	v_lshl_add_u32 v246, v244, 7, v246
	v_add_u32_e32 v249, s98, v246
	v_readlane_b32 s60, v251, 6
	v_ashrrev_i32_e32 v137, 31, v136
	s_or_b32 s56, s57, 2
	v_readlane_b32 s62, v251, 8
	v_readlane_b32 s63, v251, 9
	v_readlane_b32 s66, v251, 12
	v_readlane_b32 s67, v251, 13
	v_ashrrev_i32_e32 v139, 31, v138
	v_lshlrev_b64 v[154:155], 12, v[136:137]
	s_add_i32 s36, s36, s56
	s_mov_b64 s[62:63], s[66:67]
	v_lshlrev_b64 v[138:139], 2, v[138:139]
	v_lshl_add_u64 v[154:155], s[62:63], 0, v[154:155]
	s_ashr_i32 s37, s36, 31
	v_lshl_add_u64 v[154:155], v[154:155], 0, v[138:139]
	s_lshl_b64 s[36:37], s[36:37], 14
	v_lshl_add_u64 v[152:153], v[152:153], 0, s[36:37]
	s_and_b64 vcc, exec, s[0:1]
	s_mov_b64 s[0:1], -1
	v_readlane_b32 s61, v251, 7
	v_readlane_b32 s64, v251, 10
	v_readlane_b32 s65, v251, 11
	s_waitcnt vmcnt(15)
	v_lshlrev_b32_e32 v156, 16, v162
	v_and_b32_e32 v157, 0xffff0000, v162
	v_lshlrev_b32_e32 v148, 16, v163
	v_and_b32_e32 v149, 0xffff0000, v163
	v_lshlrev_b32_e32 v158, 16, v164
	v_and_b32_e32 v159, 0xffff0000, v164
	v_lshlrev_b32_e32 v150, 16, v165
	v_and_b32_e32 v151, 0xffff0000, v165
	v_pk_add_f32 v[126:127], v[126:127], v[148:149]
	v_pk_add_f32 v[124:125], v[124:125], v[156:157]
	v_pk_add_f32 v[122:123], v[122:123], v[150:151]
	v_pk_add_f32 v[120:121], v[120:121], v[158:159]
	s_nop 0
	v_readfirstlane_b32 s98, v154
	v_readfirstlane_b32 s99, v155
	ds_write_b128 v248, v[124:127]
	ds_write_b128 v248, v[120:123] offset:16
	ds_read_b128 v[232:235], v249
	ds_read_b128 v[236:239], v249 offset:1024
	s_nop 0
	v_or_b32_e32 v124, 16, v136
	v_lshrrev_b32_e32 v125, 3, v124
	v_and_or_b32 v125, v125, 10, s55
	v_lshlrev_b32_e32 v125, 10, v125
	v_bitop3_b32 v130, v147, v125, v160 bitop3:0xde
	v_lshl_add_u64 v[126:127], s[30:31], 0, v[130:131]
	v_lshl_add_u64 v[148:149], v[126:127], 0, s[12:13]
	v_ashrrev_i32_e32 v125, 31, v124
	s_waitcnt vmcnt(14)
	v_lshlrev_b32_e32 v150, 16, v166
	v_and_b32_e32 v151, 0xffff0000, v166
	v_lshlrev_b32_e32 v120, 16, v167
	v_and_b32_e32 v121, 0xffff0000, v167
	v_lshlrev_b32_e32 v152, 16, v168
	v_and_b32_e32 v153, 0xffff0000, v168
	v_lshlrev_b32_e32 v122, 16, v169
	v_and_b32_e32 v123, 0xffff0000, v169
	v_pk_add_f32 v[118:119], v[118:119], v[120:121]
	v_pk_add_f32 v[116:117], v[116:117], v[150:151]
	v_pk_add_f32 v[114:115], v[114:115], v[122:123]
	v_pk_add_f32 v[112:113], v[112:113], v[152:153]
	ds_write_b128 v248, v[116:119]
	ds_write_b128 v248, v[112:115] offset:16
	ds_read_b128 v[240:243], v249
	ds_read_b128 v[244:247], v249 offset:1024
	s_waitcnt lgkmcnt(4)
	global_store_dwordx4 v161, v[232:235], s[98:99] nt
	global_store_dwordx4 v201, v[236:239], s[98:99] nt
	s_nop 0
	v_lshlrev_b64 v[116:117], 12, v[124:125]
	v_lshl_add_u64 v[116:117], s[62:63], 0, v[116:117]
	v_lshl_add_u64 v[116:117], v[116:117], 0, v[138:139]
	v_lshl_add_u64 v[118:119], v[126:127], 0, s[36:37]
	s_waitcnt vmcnt(15)
; __host__ __device__ __forceinline__ size_t img_off(int row, int col, int nkt) { return ((size_t)((row >> 7) * nkt + (col >> 6)) << 14) + (size_t)lds_byte(row & 127, col & 63); }
;     __device__ __forceinline__ void operator()(const f32x4 (&acc)[2][2][4][2], const Unit& u, int wr, int wc, int fr, int fq) const {
;     ...
;             for (int m = 0; m < 4; ++m) { const int row = row0 + ai * HALF + m * 16; const size_t off = (size_t)row * 1024 + col0;
; #pragma unroll
;                 for (int bj = 0; bj < 2; ++bj) { const u32x4 xb = __builtin_nontemporal_load((const u32x4*)(x1b + img_off(row, col0 + bj * HALF, 16))); float* p = y + off + bj * HALF;
;                     const f32x4 x0 = (f32x4){__builtin_bit_cast(float, xb.x << 16), __builtin_bit_cast(float, xb.x & 0xffff0000u), __builtin_bit_cast(float, xb.y << 16), __builtin_bit_cast(float, xb.y & 0xffff0000u)};
;                     const f32x4 x1 = (f32x4){__builtin_bit_cast(float, xb.z << 16), __builtin_bit_cast(float, xb.z & 0xffff0000u), __builtin_bit_cast(float, xb.w << 16), __builtin_bit_cast(float, xb.w & 0xffff0000u)};
;                     __builtin_nontemporal_store(acc[ai][bj][m][0] + x0, (f32x4*)p); __builtin_nontemporal_store(acc[ai][bj][m][1] + x1, (f32x4*)(p + 4)); } }
	v_lshlrev_b32_e32 v120, 16, v170
	v_and_b32_e32 v121, 0xffff0000, v170
	v_lshlrev_b32_e32 v112, 16, v171
	v_and_b32_e32 v113, 0xffff0000, v171
	v_lshlrev_b32_e32 v122, 16, v172
	v_and_b32_e32 v123, 0xffff0000, v172
	v_lshlrev_b32_e32 v114, 16, v173
	v_and_b32_e32 v115, 0xffff0000, v173
	v_pk_add_f32 v[110:111], v[110:111], v[112:113]
	v_pk_add_f32 v[108:109], v[108:109], v[120:121]
	v_pk_add_f32 v[106:107], v[106:107], v[114:115]
	v_pk_add_f32 v[104:105], v[104:105], v[122:123]
	s_nop 0
	v_readfirstlane_b32 s100, v116
	v_readfirstlane_b32 s101, v117
	ds_write_b128 v248, v[108:111]
	ds_write_b128 v248, v[104:107] offset:16
	ds_read_b128 v[232:235], v249
	ds_read_b128 v[236:239], v249 offset:1024
	s_waitcnt lgkmcnt(4)
	global_store_dwordx4 v161, v[240:243], s[98:99] offset:512 nt
	global_store_dwordx4 v201, v[244:247], s[98:99] offset:512 nt
	s_nop 0
	v_or_b32_e32 v108, 32, v136
	v_lshrrev_b32_e32 v109, 3, v108
	v_and_or_b32 v109, v109, 12, s55
	v_lshlrev_b32_e32 v109, 10, v109
	v_bitop3_b32 v130, v147, v109, v160 bitop3:0xde
	v_lshl_add_u64 v[110:111], s[30:31], 0, v[130:131]
	v_lshl_add_u64 v[112:113], v[110:111], 0, s[12:13]
	v_ashrrev_i32_e32 v109, 31, v108
	s_waitcnt vmcnt(16)
	v_lshlrev_b32_e32 v114, 16, v174
	v_and_b32_e32 v115, 0xffff0000, v174
	v_lshlrev_b32_e32 v104, 16, v175
	v_and_b32_e32 v105, 0xffff0000, v175
	v_lshlrev_b32_e32 v118, 16, v176
	v_and_b32_e32 v119, 0xffff0000, v176
	v_lshlrev_b32_e32 v106, 16, v177
	v_and_b32_e32 v107, 0xffff0000, v177
	v_pk_add_f32 v[102:103], v[102:103], v[104:105]
	v_pk_add_f32 v[100:101], v[100:101], v[114:115]
	v_pk_add_f32 v[98:99], v[98:99], v[106:107]
	v_pk_add_f32 v[96:97], v[96:97], v[118:119]
	ds_write_b128 v248, v[100:103]
	ds_write_b128 v248, v[96:99] offset:16
	ds_read_b128 v[240:243], v249
	ds_read_b128 v[244:247], v249 offset:1024
	s_waitcnt lgkmcnt(4)
	global_store_dwordx4 v161, v[232:235], s[100:101] nt
	global_store_dwordx4 v201, v[236:239], s[100:101] nt
	s_nop 0
	v_lshlrev_b64 v[100:101], 12, v[108:109]
	v_lshl_add_u64 v[100:101], s[62:63], 0, v[100:101]
	v_lshl_add_u64 v[100:101], v[100:101], 0, v[138:139]
	v_lshl_add_u64 v[102:103], v[110:111], 0, s[36:37]
	s_waitcnt vmcnt(17)
	v_lshlrev_b32_e32 v104, 16, v178
	v_and_b32_e32 v105, 0xffff0000, v178
	v_lshlrev_b32_e32 v96, 16, v179
	v_and_b32_e32 v97, 0xffff0000, v179
	v_lshlrev_b32_e32 v106, 16, v180
	v_and_b32_e32 v107, 0xffff0000, v180
	v_lshlrev_b32_e32 v98, 16, v181
	v_and_b32_e32 v99, 0xffff0000, v181
	v_pk_add_f32 v[94:95], v[94:95], v[96:97]
	v_pk_add_f32 v[92:93], v[92:93], v[104:105]
	v_pk_add_f32 v[90:91], v[90:91], v[98:99]
	v_pk_add_f32 v[88:89], v[88:89], v[106:107]
	s_nop 0
	v_readfirstlane_b32 s98, v100
	v_readfirstlane_b32 s99, v101
	ds_write_b128 v248, v[92:95]
	ds_write_b128 v248, v[88:91] offset:16
	ds_read_b128 v[232:235], v249
	ds_read_b128 v[236:239], v249 offset:1024
	s_waitcnt lgkmcnt(4)
	global_store_dwordx4 v161, v[240:243], s[100:101] offset:512 nt
	global_store_dwordx4 v201, v[244:247], s[100:101] offset:512 nt
	s_nop 0
	v_or_b32_e32 v92, 48, v136
	v_lshrrev_b32_e32 v93, 3, v92
	v_and_or_b32 v93, v93, 14, s55
	v_lshlrev_b32_e32 v93, 10, v93
	v_bitop3_b32 v130, v147, v93, v160 bitop3:0xde
	v_lshl_add_u64 v[94:95], s[30:31], 0, v[130:131]
	v_lshl_add_u64 v[96:97], v[94:95], 0, s[12:13]
	v_ashrrev_i32_e32 v93, 31, v92
	s_waitcnt vmcnt(18)
	v_lshlrev_b32_e32 v98, 16, v182
	v_and_b32_e32 v99, 0xffff0000, v182
	v_lshlrev_b32_e32 v88, 16, v183
	v_and_b32_e32 v89, 0xffff0000, v183
	v_lshlrev_b32_e32 v102, 16, v184
	v_and_b32_e32 v103, 0xffff0000, v184
	v_lshlrev_b32_e32 v90, 16, v185
	v_and_b32_e32 v91, 0xffff0000, v185
	v_pk_add_f32 v[86:87], v[86:87], v[88:89]
	v_pk_add_f32 v[84:85], v[84:85], v[98:99]
	v_pk_add_f32 v[82:83], v[82:83], v[90:91]
	v_pk_add_f32 v[80:81], v[80:81], v[102:103]
	ds_write_b128 v248, v[84:87]
	ds_write_b128 v248, v[80:83] offset:16
	ds_read_b128 v[240:243], v249
	ds_read_b128 v[244:247], v249 offset:1024
	s_waitcnt lgkmcnt(4)
	global_store_dwordx4 v161, v[232:235], s[98:99] nt
	global_store_dwordx4 v201, v[236:239], s[98:99] nt
	s_nop 0
	v_lshlrev_b64 v[84:85], 12, v[92:93]
	v_lshl_add_u64 v[84:85], s[62:63], 0, v[84:85]
	v_lshl_add_u64 v[84:85], v[84:85], 0, v[138:139]
	v_lshl_add_u64 v[86:87], v[94:95], 0, s[36:37]
	s_waitcnt vmcnt(19)
	v_lshlrev_b32_e32 v88, 16, v186
	v_and_b32_e32 v89, 0xffff0000, v186
	v_lshlrev_b32_e32 v80, 16, v187
	v_and_b32_e32 v81, 0xffff0000, v187
	v_lshlrev_b32_e32 v90, 16, v188
	v_and_b32_e32 v91, 0xffff0000, v188
	v_lshlrev_b32_e32 v82, 16, v189
	v_and_b32_e32 v83, 0xffff0000, v189
	v_pk_add_f32 v[78:79], v[78:79], v[80:81]
	v_pk_add_f32 v[76:77], v[76:77], v[88:89]
	v_pk_add_f32 v[74:75], v[74:75], v[82:83]
	v_pk_add_f32 v[72:73], v[72:73], v[90:91]
	s_nop 0
	v_readfirstlane_b32 s100, v84
	v_readfirstlane_b32 s101, v85
	ds_write_b128 v248, v[76:79]
	ds_write_b128 v248, v[72:75] offset:16
	ds_read_b128 v[232:235], v249
	ds_read_b128 v[236:239], v249 offset:1024
	s_waitcnt lgkmcnt(4)
	global_store_dwordx4 v161, v[240:243], s[98:99] offset:512 nt
	global_store_dwordx4 v201, v[244:247], s[98:99] offset:512 nt
	s_nop 0
	v_add_u32_e32 v78, 0x80, v136
	v_ashrrev_i32_e32 v72, 3, v78
	v_lshlrev_b32_e32 v73, 6, v78
	v_lshlrev_b32_e32 v79, 2, v78
	v_and_b32_e32 v90, -16, v72
	v_and_or_b32 v80, v73, s48, v146
	v_and_b32_e32 v79, 32, v79
	v_add_u32_e32 v72, s57, v90
	v_ashrrev_i32_e32 v73, 31, v72
	v_bitop3_b32 v130, v80, s58, v79 bitop3:0xde
	v_lshlrev_b64 v[72:73], 14, v[72:73]
	v_lshl_add_u64 v[80:81], s[30:31], 0, v[130:131]
	v_lshl_add_u64 v[82:83], v[80:81], 0, v[72:73]
	v_ashrrev_i32_e32 v79, 31, v78
	s_waitcnt vmcnt(20)
; __host__ __device__ __forceinline__ size_t img_off(int row, int col, int nkt) { return ((size_t)((row >> 7) * nkt + (col >> 6)) << 14) + (size_t)lds_byte(row & 127, col & 63); }
;     __device__ __forceinline__ void operator()(const f32x4 (&acc)[2][2][4][2], const Unit& u, int wr, int wc, int fr, int fq) const {
;     ...
;             for (int m = 0; m < 4; ++m) { const int row = row0 + ai * HALF + m * 16; const size_t off = (size_t)row * 1024 + col0;
; #pragma unroll
;                 for (int bj = 0; bj < 2; ++bj) { const u32x4 xb = __builtin_nontemporal_load((const u32x4*)(x1b + img_off(row, col0 + bj * HALF, 16))); float* p = y + off + bj * HALF;
;                     const f32x4 x0 = (f32x4){__builtin_bit_cast(float, xb.x << 16), __builtin_bit_cast(float, xb.x & 0xffff0000u), __builtin_bit_cast(float, xb.y << 16), __builtin_bit_cast(float, xb.y & 0xffff0000u)};
;                     const f32x4 x1 = (f32x4){__builtin_bit_cast(float, xb.z << 16), __builtin_bit_cast(float, xb.z & 0xffff0000u), __builtin_bit_cast(float, xb.w << 16), __builtin_bit_cast(float, xb.w & 0xffff0000u)};
;                     __builtin_nontemporal_store(acc[ai][bj][m][0] + x0, (f32x4*)p); __builtin_nontemporal_store(acc[ai][bj][m][1] + x1, (f32x4*)(p + 4)); } }
	v_lshlrev_b32_e32 v86, 16, v190
	v_and_b32_e32 v87, 0xffff0000, v190
	v_lshlrev_b32_e32 v74, 16, v191
	v_and_b32_e32 v75, 0xffff0000, v191
	v_lshlrev_b32_e32 v88, 16, v192
	v_and_b32_e32 v89, 0xffff0000, v192
	v_lshlrev_b32_e32 v76, 16, v193
	v_and_b32_e32 v77, 0xffff0000, v193
	v_pk_add_f32 v[70:71], v[70:71], v[74:75]
	v_pk_add_f32 v[68:69], v[68:69], v[86:87]
	v_pk_add_f32 v[66:67], v[66:67], v[76:77]
	v_pk_add_f32 v[64:65], v[64:65], v[88:89]
	ds_write_b128 v248, v[68:71]
	ds_write_b128 v248, v[64:67] offset:16
	ds_read_b128 v[240:243], v249
	ds_read_b128 v[244:247], v249 offset:1024
	s_waitcnt lgkmcnt(4)
	global_store_dwordx4 v161, v[232:235], s[100:101] nt
	global_store_dwordx4 v201, v[236:239], s[100:101] nt
	s_nop 0
	v_add_u32_e32 v70, s56, v90
	v_lshlrev_b64 v[64:65], 12, v[78:79]
	v_lshl_add_u64 v[64:65], s[62:63], 0, v[64:65]
	v_ashrrev_i32_e32 v71, 31, v70
	v_lshl_add_u64 v[74:75], v[64:65], 0, v[138:139]
	v_lshlrev_b64 v[64:65], 14, v[70:71]
	v_lshl_add_u64 v[70:71], v[80:81], 0, v[64:65]
	s_waitcnt vmcnt(21)
	v_lshlrev_b32_e32 v76, 16, v194
	v_and_b32_e32 v77, 0xffff0000, v194
	v_lshlrev_b32_e32 v66, 16, v195
	v_and_b32_e32 v67, 0xffff0000, v195
	v_lshlrev_b32_e32 v78, 16, v196
	v_and_b32_e32 v79, 0xffff0000, v196
	v_lshlrev_b32_e32 v68, 16, v197
	v_and_b32_e32 v69, 0xffff0000, v197
	v_pk_add_f32 v[62:63], v[62:63], v[66:67]
	v_pk_add_f32 v[60:61], v[60:61], v[76:77]
	v_pk_add_f32 v[58:59], v[58:59], v[68:69]
	v_pk_add_f32 v[56:57], v[56:57], v[78:79]
	s_nop 0
	v_readfirstlane_b32 s98, v74
	v_readfirstlane_b32 s99, v75
	ds_write_b128 v248, v[60:63]
	ds_write_b128 v248, v[56:59] offset:16
	ds_read_b128 v[232:235], v249
	ds_read_b128 v[236:239], v249 offset:1024
	s_waitcnt lgkmcnt(4)
	global_store_dwordx4 v161, v[240:243], s[100:101] offset:512 nt
	global_store_dwordx4 v201, v[244:247], s[100:101] offset:512 nt
	s_nop 0
	v_add_u32_e32 v60, 0x90, v136
	v_lshrrev_b32_e32 v61, 3, v60
	v_lshlrev_b32_e32 v62, 6, v60
	v_lshlrev_b32_e32 v63, 2, v60
	v_and_or_b32 v61, v61, 10, s55
	v_and_or_b32 v62, v62, s48, v146
	v_and_b32_e32 v63, 32, v63
	v_lshlrev_b32_e32 v61, 10, v61
	v_bitop3_b32 v130, v62, v61, v63 bitop3:0xde
	v_lshl_add_u64 v[62:63], s[30:31], 0, v[130:131]
	v_lshl_add_u64 v[66:67], v[62:63], 0, v[72:73]
	v_ashrrev_i32_e32 v61, 31, v60
	s_waitcnt vmcnt(22)
	v_lshlrev_b32_e32 v68, 16, v202
	v_and_b32_e32 v69, 0xffff0000, v202
	v_lshlrev_b32_e32 v56, 16, v203
	v_and_b32_e32 v57, 0xffff0000, v203
	v_lshlrev_b32_e32 v70, 16, v204
	v_and_b32_e32 v71, 0xffff0000, v204
	v_lshlrev_b32_e32 v58, 16, v205
	v_and_b32_e32 v59, 0xffff0000, v205
	v_pk_add_f32 v[54:55], v[54:55], v[56:57]
	v_pk_add_f32 v[52:53], v[52:53], v[68:69]
	v_pk_add_f32 v[50:51], v[50:51], v[58:59]
	v_pk_add_f32 v[48:49], v[48:49], v[70:71]
	ds_write_b128 v248, v[52:55]
	ds_write_b128 v248, v[48:51] offset:16
	ds_read_b128 v[240:243], v249
	ds_read_b128 v[244:247], v249 offset:1024
	s_waitcnt lgkmcnt(4)
	global_store_dwordx4 v161, v[232:235], s[98:99] nt
	global_store_dwordx4 v201, v[236:239], s[98:99] nt
	s_nop 0
	v_lshlrev_b64 v[52:53], 12, v[60:61]
	v_lshl_add_u64 v[52:53], s[62:63], 0, v[52:53]
	v_lshl_add_u64 v[52:53], v[52:53], 0, v[138:139]
	v_lshl_add_u64 v[54:55], v[62:63], 0, v[64:65]
	s_waitcnt vmcnt(23)
	v_lshlrev_b32_e32 v56, 16, v206
	v_and_b32_e32 v57, 0xffff0000, v206
	v_lshlrev_b32_e32 v48, 16, v207
	v_and_b32_e32 v49, 0xffff0000, v207
	v_lshlrev_b32_e32 v58, 16, v208
	v_and_b32_e32 v59, 0xffff0000, v208
	v_lshlrev_b32_e32 v50, 16, v209
	v_and_b32_e32 v51, 0xffff0000, v209
	v_pk_add_f32 v[46:47], v[46:47], v[48:49]
	v_pk_add_f32 v[44:45], v[44:45], v[56:57]
	v_pk_add_f32 v[42:43], v[42:43], v[50:51]
	v_pk_add_f32 v[40:41], v[40:41], v[58:59]
	s_nop 0
	v_readfirstlane_b32 s100, v52
	v_readfirstlane_b32 s101, v53
	ds_write_b128 v248, v[44:47]
	ds_write_b128 v248, v[40:43] offset:16
	ds_read_b128 v[232:235], v249
	ds_read_b128 v[236:239], v249 offset:1024
	s_waitcnt lgkmcnt(4)
	global_store_dwordx4 v161, v[240:243], s[98:99] offset:512 nt
	global_store_dwordx4 v201, v[244:247], s[98:99] offset:512 nt
	s_nop 0
	v_add_u32_e32 v44, 0xa0, v136
	v_lshrrev_b32_e32 v45, 3, v44
	v_lshlrev_b32_e32 v46, 6, v44
	v_lshlrev_b32_e32 v47, 2, v44
	v_and_or_b32 v45, v45, 12, s55
	v_and_or_b32 v46, v46, s48, v146
	v_and_b32_e32 v47, 32, v47
	v_lshlrev_b32_e32 v45, 10, v45
	v_bitop3_b32 v130, v46, v45, v47 bitop3:0xde
	v_lshl_add_u64 v[46:47], s[30:31], 0, v[130:131]
	v_lshl_add_u64 v[48:49], v[46:47], 0, v[72:73]
	v_ashrrev_i32_e32 v45, 31, v44
	s_waitcnt vmcnt(24)
; __host__ __device__ __forceinline__ size_t img_off(int row, int col, int nkt) { return ((size_t)((row >> 7) * nkt + (col >> 6)) << 14) + (size_t)lds_byte(row & 127, col & 63); }
;     __device__ __forceinline__ void operator()(const f32x4 (&acc)[2][2][4][2], const Unit& u, int wr, int wc, int fr, int fq) const {
;     ...
;             for (int m = 0; m < 4; ++m) { const int row = row0 + ai * HALF + m * 16; const size_t off = (size_t)row * 1024 + col0;
; #pragma unroll
;                 for (int bj = 0; bj < 2; ++bj) { const u32x4 xb = __builtin_nontemporal_load((const u32x4*)(x1b + img_off(row, col0 + bj * HALF, 16))); float* p = y + off + bj * HALF;
;                     const f32x4 x0 = (f32x4){__builtin_bit_cast(float, xb.x << 16), __builtin_bit_cast(float, xb.x & 0xffff0000u), __builtin_bit_cast(float, xb.y << 16), __builtin_bit_cast(float, xb.y & 0xffff0000u)};
;                     const f32x4 x1 = (f32x4){__builtin_bit_cast(float, xb.z << 16), __builtin_bit_cast(float, xb.z & 0xffff0000u), __builtin_bit_cast(float, xb.w << 16), __builtin_bit_cast(float, xb.w & 0xffff0000u)};
;                     __builtin_nontemporal_store(acc[ai][bj][m][0] + x0, (f32x4*)p); __builtin_nontemporal_store(acc[ai][bj][m][1] + x1, (f32x4*)(p + 4)); } }
	v_lshlrev_b32_e32 v50, 16, v210
	v_and_b32_e32 v51, 0xffff0000, v210
	v_lshlrev_b32_e32 v40, 16, v211
	v_and_b32_e32 v41, 0xffff0000, v211
	v_lshlrev_b32_e32 v54, 16, v212
	v_and_b32_e32 v55, 0xffff0000, v212
	v_lshlrev_b32_e32 v42, 16, v213
	v_and_b32_e32 v43, 0xffff0000, v213
	v_pk_add_f32 v[38:39], v[38:39], v[40:41]
	v_pk_add_f32 v[36:37], v[36:37], v[50:51]
	v_pk_add_f32 v[34:35], v[34:35], v[42:43]
	v_pk_add_f32 v[32:33], v[32:33], v[54:55]
	ds_write_b128 v248, v[36:39]
	ds_write_b128 v248, v[32:35] offset:16
	ds_read_b128 v[240:243], v249
	ds_read_b128 v[244:247], v249 offset:1024
	s_waitcnt lgkmcnt(4)
	global_store_dwordx4 v161, v[232:235], s[100:101] nt
	global_store_dwordx4 v201, v[236:239], s[100:101] nt
	s_nop 0
	v_lshlrev_b64 v[36:37], 12, v[44:45]
	v_lshl_add_u64 v[36:37], s[62:63], 0, v[36:37]
	v_lshl_add_u64 v[36:37], v[36:37], 0, v[138:139]
	v_lshl_add_u64 v[38:39], v[46:47], 0, v[64:65]
	s_waitcnt vmcnt(25)
	v_lshlrev_b32_e32 v40, 16, v214
	v_and_b32_e32 v41, 0xffff0000, v214
	v_lshlrev_b32_e32 v32, 16, v215
	v_and_b32_e32 v33, 0xffff0000, v215
	v_lshlrev_b32_e32 v42, 16, v216
	v_and_b32_e32 v43, 0xffff0000, v216
	v_lshlrev_b32_e32 v34, 16, v217
	v_and_b32_e32 v35, 0xffff0000, v217
	v_pk_add_f32 v[30:31], v[30:31], v[32:33]
	v_pk_add_f32 v[28:29], v[28:29], v[40:41]
	v_pk_add_f32 v[26:27], v[26:27], v[34:35]
	v_pk_add_f32 v[24:25], v[24:25], v[42:43]
	s_nop 0
	v_readfirstlane_b32 s98, v36
	v_readfirstlane_b32 s99, v37
	ds_write_b128 v248, v[28:31]
	ds_write_b128 v248, v[24:27] offset:16
	ds_read_b128 v[232:235], v249
	ds_read_b128 v[236:239], v249 offset:1024
	s_waitcnt lgkmcnt(4)
	global_store_dwordx4 v161, v[240:243], s[100:101] offset:512 nt
	global_store_dwordx4 v201, v[244:247], s[100:101] offset:512 nt
	s_nop 0
	v_add_u32_e32 v28, 0xb0, v136
	v_lshrrev_b32_e32 v29, 3, v28
	v_lshlrev_b32_e32 v30, 6, v28
	v_lshlrev_b32_e32 v31, 2, v28
	v_and_or_b32 v29, v29, 14, s55
	v_and_or_b32 v30, v30, s48, v146
	v_and_b32_e32 v31, 32, v31
	v_lshlrev_b32_e32 v29, 10, v29
	v_bitop3_b32 v130, v30, v29, v31 bitop3:0xde
	v_lshl_add_u64 v[30:31], s[30:31], 0, v[130:131]
	v_lshl_add_u64 v[32:33], v[30:31], 0, v[72:73]
	v_ashrrev_i32_e32 v29, 31, v28
	s_waitcnt vmcnt(26)
	v_lshlrev_b32_e32 v34, 16, v218
	v_and_b32_e32 v35, 0xffff0000, v218
	v_lshlrev_b32_e32 v24, 16, v219
	v_and_b32_e32 v25, 0xffff0000, v219
	v_lshlrev_b32_e32 v38, 16, v220
	v_and_b32_e32 v39, 0xffff0000, v220
	v_lshlrev_b32_e32 v26, 16, v221
	v_and_b32_e32 v27, 0xffff0000, v221
	v_pk_add_f32 v[22:23], v[22:23], v[24:25]
	v_pk_add_f32 v[20:21], v[20:21], v[34:35]
	v_pk_add_f32 v[18:19], v[18:19], v[26:27]
	v_pk_add_f32 v[16:17], v[16:17], v[38:39]
	ds_write_b128 v248, v[20:23]
	ds_write_b128 v248, v[16:19] offset:16
	ds_read_b128 v[240:243], v249
	ds_read_b128 v[244:247], v249 offset:1024
	s_waitcnt lgkmcnt(4)
	global_store_dwordx4 v161, v[232:235], s[98:99] nt
	global_store_dwordx4 v201, v[236:239], s[98:99] nt
	s_nop 0
	v_lshlrev_b64 v[20:21], 12, v[28:29]
	v_lshl_add_u64 v[20:21], s[62:63], 0, v[20:21]
	v_lshl_add_u64 v[20:21], v[20:21], 0, v[138:139]
	v_lshl_add_u64 v[22:23], v[30:31], 0, v[64:65]
	s_waitcnt vmcnt(27)
	v_lshlrev_b32_e32 v24, 16, v222
	v_and_b32_e32 v25, 0xffff0000, v222
	v_lshlrev_b32_e32 v16, 16, v223
	v_and_b32_e32 v17, 0xffff0000, v223
	v_lshlrev_b32_e32 v26, 16, v224
	v_and_b32_e32 v27, 0xffff0000, v224
	v_lshlrev_b32_e32 v18, 16, v225
	v_and_b32_e32 v19, 0xffff0000, v225
	v_pk_add_f32 v[14:15], v[14:15], v[16:17]
	v_pk_add_f32 v[12:13], v[12:13], v[24:25]
	v_pk_add_f32 v[10:11], v[10:11], v[18:19]
	v_pk_add_f32 v[8:9], v[8:9], v[26:27]
	s_nop 0
	v_readfirstlane_b32 s100, v20
	v_readfirstlane_b32 s101, v21
	ds_write_b128 v248, v[12:15]
	ds_write_b128 v248, v[8:11] offset:16
	ds_read_b128 v[232:235], v249
	ds_read_b128 v[236:239], v249 offset:1024
	s_waitcnt lgkmcnt(4)
	global_store_dwordx4 v161, v[240:243], s[98:99] offset:512 nt
	global_store_dwordx4 v201, v[244:247], s[98:99] offset:512 nt
	s_nop 0
	s_waitcnt vmcnt(28)
	v_lshlrev_b32_e32 v12, 16, v226
	v_and_b32_e32 v13, 0xffff0000, v226
	v_lshlrev_b32_e32 v8, 16, v227
	v_and_b32_e32 v9, 0xffff0000, v227
	v_lshlrev_b32_e32 v14, 16, v228
	v_and_b32_e32 v15, 0xffff0000, v228
	v_lshlrev_b32_e32 v10, 16, v229
	v_and_b32_e32 v11, 0xffff0000, v229
	v_pk_add_f32 v[6:7], v[6:7], v[8:9]
	v_pk_add_f32 v[4:5], v[4:5], v[12:13]
	v_pk_add_f32 v[2:3], v[2:3], v[10:11]
	v_pk_add_f32 v[0:1], v[0:1], v[14:15]
	ds_write_b128 v248, v[4:7]
	ds_write_b128 v248, v[0:3] offset:16
	ds_read_b128 v[240:243], v249
	ds_read_b128 v[244:247], v249 offset:1024
	s_waitcnt lgkmcnt(4)
	global_store_dwordx4 v161, v[232:235], s[100:101] nt
	global_store_dwordx4 v201, v[236:239], s[100:101] nt
	s_waitcnt lgkmcnt(0)
	global_store_dwordx4 v161, v[240:243], s[100:101] offset:512 nt
	global_store_dwordx4 v201, v[244:247], s[100:101] offset:512 nt
	s_cbranch_vccnz .LBB0_1412
	s_andn2_b64 vcc, exec, s[18:19]
	s_cbranch_vccnz .LBB0_1411
	s_barrier
	s_branch .LBB0_1411
